# P2 attention: one static s_setprio 1 for waves 4-7 for the whole phase (reset at phase end)
# baseline (speedup 1.0000x reference)
.LBB0_260:
	s_or_b64 exec, exec, s[4:5]
	v_readlane_b32 s0, v254, 7
	v_readlane_b32 s1, v254, 8
	s_add_u32 s52, s80, 0x14400000
	s_addc_u32 s53, s81, 0
	s_waitcnt lgkmcnt(0)
	v_cndmask_b32_e64 v1, 0, 1, s[0:1]
	v_cmp_ne_u32_e64 s[14:15], 1, v1
	s_andn2_b64 vcc, exec, s[0:1]
	s_barrier
	s_cbranch_vccnz .LBB0_317
	v_readfirstlane_b32 s0, v0
	s_cmpk_ge_u32 s0, 0x100
	s_cbranch_scc0 .Lprio_p2
	s_setprio 1
.Lprio_p2:
	s_ashr_i32 s0, s82, 3
	s_bfe_u32 s8, s82, 0x10002
	s_ashr_i32 s1, s0, 31
	s_and_b32 s6, s82, 7
	s_lshl_b32 s7, s8, 1
	s_lshl_b64 s[56:57], s[0:1], 19
	s_add_u32 s58, s80, 0xa400000
	s_addc_u32 s59, s81, 0
	s_add_u32 s60, s80, 0xc400000
	s_addc_u32 s61, s81, 0
	s_lshl_b32 s4, s6, 10
	v_sub_u32_e64 v1, s6, 4 clamp
	s_cmp_lt_u32 s6, 4
	v_mov_b32_e32 v7, v0
	v_lshlrev_b32_e32 v2, 7, v1
	s_cselect_b32 s34, s4, 0
	v_or_b32_e32 v2, s56, v2
	v_readfirstlane_b32 s4, v7
	v_mov_b32_e32 v3, s57
	s_ashr_i32 s5, s4, 6
	v_lshlrev_b64 v[4:5], 1, v[2:3]
	s_lshl_b32 s9, s5, 3
	v_bfe_u32 v2, v7, 4, 2
	v_bfe_u32 v9, v7, 2, 4
	v_or_b32_e32 v6, s9, v2
	s_lshl_b32 s10, s5, 11
	v_bitop3_b32 v9, s9, -13, v9 bitop3:0xc8
	v_lshrrev_b32_e32 v11, 1, v7
	s_lshl_b32 s9, s5, 2
	s_add_i32 s10, s10, 0
	v_and_b32_e32 v11, 8, v11
	s_and_b32 s9, s9, 4
	v_or3_b32 v15, v9, v11, s9
	s_add_i32 s9, s10, 0x10000
	s_add_i32 s11, s34, 0xffffff80
	v_and_b32_e32 v8, 15, v7
	v_or_b32_e32 v14, 4, v6
	s_cmp_lg_u32 s34, 0
	v_bitop3_b32 v10, v14, v8, 7 bitop3:0x6c
	v_and_b32_e32 v8, 32, v7
	v_lshlrev_b32_e32 v12, 3, v7
	s_cselect_b32 s11, s11, 0
	v_and_or_b32 v12, v12, 24, v8
	v_add_u32_e32 v8, s11, v6
	v_ashrrev_i32_e32 v9, 31, v8
	s_add_i32 s12, s7, 7
	v_lshl_add_u64 v[178:179], s[58:59], 0, v[4:5]
	v_bitop3_b32 v2, v2, v7, 15 bitop3:0x78
	v_lshlrev_b64 v[8:9], s12, v[8:9]
	v_mov_b32_e32 v3, 0
	v_lshl_add_u64 v[8:9], v[8:9], 1, v[178:179]
	v_lshlrev_b32_e32 v2, 4, v2
	v_lshl_add_u64 v[8:9], v[8:9], 0, v[2:3]
	s_mov_b32 m0, s10
	v_lshlrev_b32_e32 v10, 4, v10
	global_load_lds_dwordx4 v[8:9], off
	v_add_u32_e32 v8, s11, v14
	v_ashrrev_i32_e32 v9, 31, v8
	v_lshlrev_b64 v[8:9], s12, v[8:9]
	v_lshl_add_u64 v[8:9], v[8:9], 1, v[178:179]
	v_mov_b32_e32 v11, v3
	v_lshl_add_u64 v[8:9], v[8:9], 0, v[10:11]
	s_add_i32 m0, s10, 0x400
	v_lshl_add_u64 v[82:83], s[60:61], 0, v[4:5]
	global_load_lds_dwordx4 v[8:9], off
	v_add_u32_e32 v8, s11, v15
	v_ashrrev_i32_e32 v9, 31, v8
	v_lshlrev_b64 v[8:9], s12, v[8:9]
	v_lshl_add_u64 v[8:9], v[8:9], 1, v[82:83]
	v_lshlrev_b32_e32 v12, 1, v12
	v_mov_b32_e32 v13, v3
	v_lshl_add_u64 v[8:9], v[8:9], 0, v[12:13]
	s_mov_b32 m0, s9
	s_mov_b64 s[62:63], 0x80
	global_load_lds_dwordx4 v[8:9], off
	v_lshl_add_u64 v[8:9], v[8:9], 0, s[62:63]
	s_add_i32 m0, s10, 0x10400
	s_or_b32 s9, s11, 64
	global_load_lds_dwordx4 v[8:9], off
	v_add_u32_e32 v8, s9, v6
	v_ashrrev_i32_e32 v9, 31, v8
	v_lshlrev_b64 v[8:9], s12, v[8:9]
	v_lshl_add_u64 v[8:9], v[8:9], 1, v[178:179]
	s_add_i32 m0, s10, 0x4000
	v_lshl_add_u64 v[8:9], v[8:9], 0, v[2:3]
	global_load_lds_dwordx4 v[8:9], off
	v_add_u32_e32 v8, s9, v14
	v_ashrrev_i32_e32 v9, 31, v8
	v_lshlrev_b64 v[8:9], s12, v[8:9]
	v_lshl_add_u64 v[8:9], v[8:9], 1, v[178:179]
	v_lshl_add_u64 v[8:9], v[8:9], 0, v[10:11]
	s_add_i32 m0, s10, 0x4400
	v_and_b32_e32 v6, 31, v7
	global_load_lds_dwordx4 v[8:9], off
	v_add_u32_e32 v8, s9, v15
	v_ashrrev_i32_e32 v9, 31, v8
	v_lshlrev_b64 v[8:9], s12, v[8:9]
	v_lshl_add_u64 v[8:9], v[8:9], 1, v[82:83]
	s_add_i32 m0, s10, 0x14000
	v_lshl_add_u64 v[8:9], v[8:9], 0, v[12:13]
	global_load_lds_dwordx4 v[8:9], off
	v_lshl_add_u64 v[8:9], v[8:9], 0, s[62:63]
	s_add_i32 m0, s10, 0x14400
	v_or_b32_e32 v2, s34, v6
	global_load_lds_dwordx4 v[8:9], off
	v_lshl_add_u32 v10, s5, 5, v2
	v_ashrrev_i32_e32 v11, 31, v10
	v_lshl_add_u64 v[180:181], s[18:19], 0, v[4:5]
	v_bfe_u32 v8, v7, 5, 1
	v_lshlrev_b64 v[10:11], s12, v[10:11]
	v_lshl_add_u64 v[10:11], v[10:11], 1, v[180:181]
	v_lshlrev_b32_e32 v2, 4, v8
	v_lshl_add_u64 v[10:11], v[10:11], 0, v[2:3]
	global_load_dwordx4 v[146:149], v[10:11], off offset:0
	global_load_dwordx4 v[150:153], v[10:11], off offset:32
	global_load_dwordx4 v[154:157], v[10:11], off offset:64
	global_load_dwordx4 v[158:161], v[10:11], off offset:0x60
	global_load_dwordx4 v[162:165], v[10:11], off offset:0x80
	global_load_dwordx4 v[166:169], v[10:11], off offset:0xa0
	global_load_dwordx4 v[170:173], v[10:11], off offset:0xc0
	global_load_dwordx4 v[174:177], v[10:11], off offset:0xe0
	s_mov_b32 s35, 4
	s_mov_b32 s65, 0
	s_cmp_gt_u32 s4, 63
	s_cbranch_scc1 .LBB0_263
	v_and_b32_e32 v2, 63, v7
	v_lshlrev_b32_e32 v7, 2, v8
	v_mov_b32_e32 v16, 0xff800000
	v_cmp_gt_u32_e32 vcc, v6, v7
	v_or_b32_e32 v11, 2, v7
	s_mov_b32 s36, 0xff800000
	s_mov_b32 s68, 0
	v_cndmask_b32_e32 v8, 0, v16, vcc
	v_cndmask_b32_e64 v13, v16, 0, vcc
	v_cmp_gt_u32_e32 vcc, v6, v11
	v_cmp_lt_u32_e64 s[4:5], v6, v7
	v_or_b32_e32 v9, 1, v7
	v_cndmask_b32_e32 v10, 0, v16, vcc
	v_cmp_lt_u32_e32 vcc, v6, v11
	v_or_b32_e32 v15, 3, v7
	s_mov_b32 s69, s68
	s_mov_b32 s37, s36
	v_lshl_add_u32 v2, v2, 4, 0
	v_cndmask_b32_e64 v12, 0, v16, s[4:5]
	v_cmp_gt_u32_e64 s[4:5], v6, v9
	v_cndmask_b32_e32 v14, 0, v16, vcc
	v_cmp_gt_u32_e32 vcc, v6, v15
	s_mov_b32 s70, s68
	s_mov_b32 s71, s68
	v_mov_b64_e32 v[18:19], s[68:69]
	s_mov_b32 s38, s36
	s_mov_b32 s39, s36
	v_mov_b64_e32 v[22:23], s[36:37]
	v_add_u32_e32 v2, 0x20000, v2
	v_cndmask_b32_e64 v9, 0, v16, s[4:5]
	v_cndmask_b32_e32 v11, 0, v16, vcc
	v_cmp_lt_u32_e32 vcc, v6, v15
	v_mov_b64_e32 v[20:21], s[70:71]
	v_mov_b64_e32 v[24:25], s[38:39]
	v_cndmask_b32_e32 v15, 0, v16, vcc
	ds_write_b128 v2, v[18:21]
	ds_write_b128 v2, v[22:25] offset:4096
	ds_write_b128 v2, v[8:11] offset:8192
	ds_write_b128 v2, v[12:15] offset:12288
	v_or_b32_e32 v9, 8, v7
	v_cmp_gt_u32_e32 vcc, v6, v9
	v_or_b32_e32 v10, 9, v7
	v_or_b32_e32 v11, 10, v7
	v_cndmask_b32_e32 v8, 0, v16, vcc
	v_cmp_lt_u32_e32 vcc, v6, v9
	v_or_b32_e32 v15, 11, v7
	s_nop 0
	v_cndmask_b32_e32 v12, 0, v16, vcc
	v_cmp_gt_u32_e32 vcc, v6, v10
	s_nop 1
	v_cndmask_b32_e32 v9, 0, v16, vcc
	v_cmp_lt_u32_e32 vcc, v6, v10
	s_nop 1
	v_cndmask_b32_e32 v13, 0, v16, vcc
	v_cmp_gt_u32_e32 vcc, v6, v11
	s_nop 1
	v_cndmask_b32_e32 v10, 0, v16, vcc
	v_cmp_lt_u32_e32 vcc, v6, v11
	s_nop 1
	v_cndmask_b32_e32 v14, 0, v16, vcc
	v_cmp_gt_u32_e32 vcc, v6, v15
	s_nop 1
	v_cndmask_b32_e32 v11, 0, v16, vcc
	v_cmp_lt_u32_e32 vcc, v6, v15
	s_nop 1
	v_cndmask_b32_e32 v15, 0, v16, vcc
	ds_write_b128 v2, v[18:21] offset:1024
	ds_write_b128 v2, v[22:25] offset:5120
	ds_write_b128 v2, v[8:11] offset:9216
	ds_write_b128 v2, v[12:15] offset:13312
	v_or_b32_e32 v9, 16, v7
	v_cmp_gt_u32_e32 vcc, v6, v9
	v_or_b32_e32 v10, 17, v7
	v_or_b32_e32 v11, 18, v7
	v_cndmask_b32_e32 v8, 0, v16, vcc
	v_cmp_lt_u32_e32 vcc, v6, v9
	v_or_b32_e32 v15, 19, v7
	s_nop 0
	v_cndmask_b32_e32 v12, 0, v16, vcc
	v_cmp_gt_u32_e32 vcc, v6, v10
	s_nop 1
	v_cndmask_b32_e32 v9, 0, v16, vcc
	v_cmp_lt_u32_e32 vcc, v6, v10
	s_nop 1
	v_cndmask_b32_e32 v13, 0, v16, vcc
	v_cmp_gt_u32_e32 vcc, v6, v11
	s_nop 1
	v_cndmask_b32_e32 v10, 0, v16, vcc
	v_cmp_lt_u32_e32 vcc, v6, v11
	s_nop 1
	v_cndmask_b32_e32 v14, 0, v16, vcc
	v_cmp_gt_u32_e32 vcc, v6, v15
	s_nop 1
	v_cndmask_b32_e32 v11, 0, v16, vcc
	v_cmp_lt_u32_e32 vcc, v6, v15
	s_nop 1
	v_cndmask_b32_e32 v15, 0, v16, vcc
	ds_write_b128 v2, v[18:21] offset:2048
	ds_write_b128 v2, v[22:25] offset:6144
	ds_write_b128 v2, v[8:11] offset:10240
	ds_write_b128 v2, v[12:15] offset:14336
	v_or_b32_e32 v9, 24, v7
	v_cmp_gt_u32_e32 vcc, v6, v9
	v_or_b32_e32 v10, 25, v7
	v_or_b32_e32 v11, 26, v7
	v_cndmask_b32_e32 v8, 0, v16, vcc
	v_cmp_lt_u32_e32 vcc, v6, v9
	v_or_b32_e32 v7, 27, v7
	s_nop 0
	v_cndmask_b32_e32 v12, 0, v16, vcc
	v_cmp_gt_u32_e32 vcc, v6, v10
	s_nop 1
	v_cndmask_b32_e32 v9, 0, v16, vcc
	v_cmp_lt_u32_e32 vcc, v6, v10
	s_nop 1
	v_cndmask_b32_e32 v13, 0, v16, vcc
	v_cmp_gt_u32_e32 vcc, v6, v11
	s_nop 1
	v_cndmask_b32_e32 v10, 0, v16, vcc
	v_cmp_lt_u32_e32 vcc, v6, v11
	s_nop 1
	v_cndmask_b32_e32 v14, 0, v16, vcc
	v_cmp_gt_u32_e32 vcc, v6, v7
	s_nop 1
	v_cndmask_b32_e32 v11, 0, v16, vcc
	v_cmp_lt_u32_e32 vcc, v6, v7
	s_nop 1
	v_cndmask_b32_e32 v15, 0, v16, vcc
	ds_write_b128 v2, v[18:21] offset:3072
	ds_write_b128 v2, v[22:25] offset:7168
	ds_write_b128 v2, v[8:11] offset:11264
	ds_write_b128 v2, v[12:15] offset:15360

.LBB0_317:
	s_setprio 0
	s_waitcnt vmcnt(0)
	s_barrier
	s_mov_b64 s[4:5], exec
	v_readlane_b32 s0, v254, 5
	v_readlane_b32 s1, v254, 6
	s_and_b64 s[0:1], s[4:5], s[0:1]
	s_mov_b64 exec, s[0:1]
	s_cbranch_execz .LBB0_369
	s_add_i32 s0, 0, 0x27160
	v_mov_b32_e32 v1, s0
	s_waitcnt vmcnt(0) expcnt(0) lgkmcnt(0)
	ds_read_b32 v3, v1
	s_add_i32 s0, 0, 0x27164
	v_mov_b32_e32 v1, s0
	ds_read_b32 v1, v1
	s_waitcnt lgkmcnt(1)
	v_cmp_ne_u32_e32 vcc, 0, v3
	s_cbranch_vccnz .LBB0_333
	v_readlane_b32 s0, v254, 0
	v_readlane_b32 s1, v254, 1
	s_load_dwordx2 s[8:9], s[0:1], 0x4
	s_add_u32 s0, s80, 0x1200
	s_addc_u32 s1, s81, 0
	s_add_u32 s6, s80, 0x1400
	s_addc_u32 s7, s81, 0
	s_waitcnt lgkmcnt(0)
	s_mul_i32 s38, s8, s2
	s_add_u32 s8, s80, 0x1500
	s_mul_i32 s38, s38, s9
	s_addc_u32 s9, s81, 0
	s_add_u32 s10, s80, 0x1600
	s_addc_u32 s11, s81, 0
	s_add_u32 s12, s80, 0x1700
	s_addc_u32 s13, s81, 0
	s_add_u32 s20, s80, 0x1800
	s_addc_u32 s21, s81, 0
	s_add_u32 s36, s80, 0x1900
	s_addc_u32 s37, s81, 0
	s_add_u32 s40, s80, 0x1a00
	s_addc_u32 s41, s81, 0
	s_add_u32 s50, s80, 0x1b00
	s_addc_u32 s51, s81, 0
	s_add_u32 s56, s80, 0x1c00
	s_addc_u32 s57, s81, 0
	s_add_u32 s58, s80, 0x1d00
	s_addc_u32 s59, s81, 0
	s_add_u32 s60, s80, 0x1e00
	s_addc_u32 s61, s81, 0
	s_add_u32 s62, s80, 0x1f00
	s_addc_u32 s63, s81, 0
	s_add_u32 s64, s80, 0x2000
	s_addc_u32 s65, s81, 0
	s_add_u32 s66, s80, 0x2100
	s_addc_u32 s67, s81, 0
	s_add_u32 s68, s80, 0x2200
	s_addc_u32 s69, s81, 0
	s_add_u32 s70, s80, 0x2300
	s_addc_u32 s71, s81, 0
	s_mov_b32 s39, 1
	v_mov_b32_e32 v17, 0
	s_branch .LBB0_321
